# prepR meta items mapped to heads of the block's LDS-resident group (LDS LoRA path for them too); no-op waits removed in front of the scan loop
# speedup vs baseline: 1.0310x; 1.0010x over previous
; __device__ __forceinline__ unsigned pk2(float lo, float hi) { return pg8::cvt_pk_bf16(lo, hi); }
; __device__ __forceinline__ void prepR_phase(const Params& P, int wid, int G, int NGW, int lane) {
;     ...
;         for (int ks = 0; ks < 8; ++ks) {
;             const int col = 32 * ks + 8 * fq; float p[8], pp[8]; ld8(PX + (size_t)row * 256 + col, true, p); ld8(PX + (size_t)(prow < 0 ? 0 : prow) * 256 + col, prow >= 0, pp);
;             const f32x4 m0 = *(const f32x4*)(mu + 1536 + col), m1 = *(const f32x4*)(mu + 1536 + col + 4); float x[8];
; #pragma unroll
;             for (int e = 0; e < 8; ++e) { const float m = e < 4 ? m0[e & 3] : m1[e & 3]; x[e] = p[e] + (pp[e] - p[e]) * m; }
;             if (ks < 2) {
; #pragma unroll
;                 for (int e = 0; e < 8; ++e) { const float t = __expf(-2.0f * __builtin_fabsf(x[e])); const float th = (1.0f - t) * __builtin_amdgcn_rcpf(1.0f + t); x[e] = x[e] < 0.f ? -th : th; }
;             } else if (ks >= 4) {
; #pragma unroll
;                 for (int e = 0; e < 8; ++e) x[e] = __builtin_amdgcn_rcpf(1.0f + __expf(-x[e]));
;             }
;             const u32x4 w = (u32x4){pk2(x[0], x[1]), pk2(x[2], x[3]), pk2(x[4], x[5]), pk2(x[6], x[7])};
;             const bf16x8 f = __builtin_bit_cast(bf16x8, w);
;             if (ks < 2) xwf[ks] = f; else if (ks < 4) xaf[ks - 2] = f; else xgf[ks - 4] = f;
.LBB0_763:
	s_or_b64 exec, exec, s[0:1]
	s_waitcnt vmcnt(0)
	v_lshlrev_b32_e32 v122, 16, v112
	v_and_b32_e32 v112, 0xffff0000, v112
	v_lshlrev_b32_e32 v126, 16, v108
	v_and_b32_e32 v108, 0xffff0000, v108
	v_lshlrev_b32_e32 v123, 16, v113
	v_lshlrev_b32_e32 v127, 16, v109
	v_sub_f32_e32 v108, v108, v112
	v_and_b32_e32 v113, 0xffff0000, v113
	v_and_b32_e32 v109, 0xffff0000, v109
	v_fmac_f32_e32 v112, v117, v108
	v_sub_f32_e32 v108, v127, v123
	v_lshlrev_b32_e32 v124, 16, v114
	v_lshlrev_b32_e32 v128, 16, v110
	v_fmac_f32_e32 v123, v118, v108
	v_sub_f32_e32 v108, v109, v113
	v_lshlrev_b32_e32 v125, 16, v115
	v_lshlrev_b32_e32 v129, 16, v111
	v_fmac_f32_e32 v113, v119, v108
	v_sub_f32_e32 v108, v128, v124
	v_and_b32_e32 v115, 0xffff0000, v115
	v_and_b32_e32 v111, 0xffff0000, v111
	v_fmac_f32_e32 v124, v0, v108
	v_sub_f32_e32 v108, v129, v125
	v_fmac_f32_e32 v125, v2, v108
	v_sub_f32_e32 v2, v111, v115
	v_fmac_f32_e32 v115, v3, v2
	v_mul_f32_e32 v2, 0xbfb8aa3b, v115
	v_exp_f32_e32 v2, v2
	v_mul_f32_e32 v3, 0xbfb8aa3b, v125
	v_and_b32_e32 v114, 0xffff0000, v114
	v_and_b32_e32 v110, 0xffff0000, v110
	v_exp_f32_e32 v3, v3
	v_sub_f32_e32 v0, v110, v114
	v_fmac_f32_e32 v114, v1, v0
	v_add_f32_e32 v0, 1.0, v2
	v_mul_f32_e32 v1, 0xbfb8aa3b, v114
	v_rcp_f32_e32 v108, v0
	v_add_f32_e32 v0, 1.0, v3
	v_exp_f32_e32 v1, v1
	v_mul_f32_e32 v2, 0xbfb8aa3b, v124
	v_mul_f32_e32 v3, 0xbfb8aa3b, v113
	v_exp_f32_e32 v2, v2
	v_exp_f32_e32 v3, v3
	v_add_f32_e32 v1, 1.0, v1
	v_rcp_f32_e32 v109, v1
	v_add_f32_e32 v1, 1.0, v2
	v_add_f32_e32 v2, 1.0, v3
	v_mul_f32_e32 v3, 0xbfb8aa3b, v123
	v_exp_f32_e32 v3, v3
	v_rcp_f32_e32 v2, v2
	v_mul_f32_e32 v110, 0xbfb8aa3b, v112
	v_rcp_f32_e32 v112, v1
	v_add_f32_e32 v3, 1.0, v3
	v_rcp_f32_e32 v3, v3
	v_rcp_f32_e32 v113, v0
	v_sub_f32_e32 v126, v126, v122
	v_fmac_f32_e32 v122, v116, v126
	v_cvt_pk_bf16_f32 v1, v3, v2
	v_cvt_pk_bf16_f32 v2, v112, v109
	v_lshlrev_b32_e32 v112, 16, v96
	v_and_b32_e32 v96, 0xffff0000, v96
	v_lshlrev_b32_e32 v116, 16, v4
	v_and_b32_e32 v4, 0xffff0000, v4
	v_cvt_pk_bf16_f32 v3, v113, v108
	v_lshlrev_b32_e32 v113, 16, v97
	v_lshlrev_b32_e32 v117, 16, v5
	v_sub_f32_e32 v4, v4, v96
	v_and_b32_e32 v97, 0xffff0000, v97
	v_lshlrev_b32_e32 v115, 16, v99
	v_and_b32_e32 v5, 0xffff0000, v5
	v_lshlrev_b32_e32 v119, 16, v7
	v_fmac_f32_e32 v96, v101, v4
	v_sub_f32_e32 v4, v117, v113
	v_and_b32_e32 v99, 0xffff0000, v99
	v_and_b32_e32 v7, 0xffff0000, v7
	v_fmac_f32_e32 v113, v102, v4
	v_sub_f32_e32 v4, v5, v97
	v_sub_f32_e32 v5, v119, v115
	v_fmac_f32_e32 v115, v94, v5
	v_sub_f32_e32 v5, v7, v99
	v_lshlrev_b32_e32 v114, 16, v98
	v_lshlrev_b32_e32 v118, 16, v6
	v_fmac_f32_e32 v99, v95, v5
	v_and_b32_e32 v98, 0xffff0000, v98
	v_and_b32_e32 v6, 0xffff0000, v6
	v_fmac_f32_e32 v97, v103, v4
	v_sub_f32_e32 v4, v118, v114
	v_mul_f32_e32 v5, 0xbfb8aa3b, v99
	v_fmac_f32_e32 v114, v92, v4
	v_sub_f32_e32 v4, v6, v98
	v_exp_f32_e32 v5, v5
	v_mul_f32_e32 v6, 0xbfb8aa3b, v115
	v_exp_f32_e32 v6, v6
	v_fmac_f32_e32 v98, v93, v4
	v_add_f32_e32 v4, 1.0, v5
	v_mul_f32_e32 v5, 0xbfb8aa3b, v98
	v_rcp_f32_e32 v7, v4
	v_add_f32_e32 v4, 1.0, v6
	v_exp_f32_e32 v5, v5
	v_mul_f32_e32 v6, 0xbfb8aa3b, v114
	v_mul_f32_e32 v92, 0xbfb8aa3b, v97
	v_exp_f32_e32 v6, v6
	v_exp_f32_e32 v92, v92
	v_add_f32_e32 v5, 1.0, v5
	v_rcp_f32_e32 v93, v5
	v_add_f32_e32 v5, 1.0, v6
	v_add_f32_e32 v6, 1.0, v92
	v_mul_f32_e32 v92, 0xbfb8aa3b, v113
	v_sub_f32_e32 v116, v116, v112
	v_exp_f32_e32 v92, v92
	v_fmac_f32_e32 v112, v100, v116
	v_mul_f32_e32 v94, 0xbfb8aa3b, v96
	v_mul_f32_e32 v95, 0xbfb8aa3b, v112
	v_exp_f32_e32 v94, v94
	v_exp_f32_e32 v95, v95
	v_add_f32_e32 v92, 1.0, v92
	v_rcp_f32_e32 v6, v6
	v_rcp_f32_e32 v92, v92
	v_rcp_f32_e32 v96, v5
	v_rcp_f32_e32 v97, v4
	v_add_f32_e32 v94, 1.0, v94
	v_add_f32_e32 v95, 1.0, v95
	v_rcp_f32_e32 v94, v94
	v_rcp_f32_e32 v95, v95
	v_cvt_pk_bf16_f32 v5, v92, v6
	v_cvt_pk_bf16_f32 v6, v96, v93
	v_lshlrev_b32_e32 v92, 16, v84
	v_and_b32_e32 v84, 0xffff0000, v84
	v_lshlrev_b32_e32 v96, 16, v80
	v_and_b32_e32 v80, 0xffff0000, v80
	v_cvt_pk_bf16_f32 v7, v97, v7
	v_lshlrev_b32_e32 v93, 16, v85
	v_lshlrev_b32_e32 v97, 16, v81
	v_sub_f32_e32 v80, v80, v84
	v_and_b32_e32 v85, 0xffff0000, v85
	v_and_b32_e32 v81, 0xffff0000, v81
	v_fmac_f32_e32 v84, v89, v80
	v_sub_f32_e32 v80, v97, v93
	v_cvt_pk_bf16_f32 v4, v95, v94
	v_lshlrev_b32_e32 v94, 16, v86
	v_lshlrev_b32_e32 v98, 16, v82
	v_fmac_f32_e32 v93, v90, v80
	v_sub_f32_e32 v80, v81, v85
	v_lshlrev_b32_e32 v95, 16, v87
	v_lshlrev_b32_e32 v99, 16, v83
	v_fmac_f32_e32 v85, v91, v80
	v_sub_f32_e32 v80, v98, v94
	v_and_b32_e32 v87, 0xffff0000, v87
	v_and_b32_e32 v83, 0xffff0000, v83
	v_fmac_f32_e32 v94, v8, v80
	v_sub_f32_e32 v80, v99, v95
	v_fmac_f32_e32 v95, v10, v80
	v_sub_f32_e32 v10, v83, v87
	v_fmac_f32_e32 v87, v11, v10
	v_mul_f32_e32 v10, 0xbfb8aa3b, v87
	v_exp_f32_e32 v10, v10
	v_mul_f32_e32 v11, 0xbfb8aa3b, v95
	v_and_b32_e32 v86, 0xffff0000, v86
	v_and_b32_e32 v82, 0xffff0000, v82
	v_exp_f32_e32 v11, v11
	v_sub_f32_e32 v8, v82, v86
	v_fmac_f32_e32 v86, v9, v8
	v_add_f32_e32 v8, 1.0, v10
	v_mul_f32_e32 v9, 0xbfb8aa3b, v86
	v_rcp_f32_e32 v80, v8
	v_add_f32_e32 v8, 1.0, v11
	v_exp_f32_e32 v9, v9
	v_mul_f32_e32 v10, 0xbfb8aa3b, v94
	v_mul_f32_e32 v11, 0xbfb8aa3b, v85
	v_exp_f32_e32 v10, v10
	v_exp_f32_e32 v11, v11
	v_add_f32_e32 v9, 1.0, v9
	v_sub_f32_e32 v96, v96, v92
	v_rcp_f32_e32 v81, v9
	v_add_f32_e32 v9, 1.0, v10
	v_add_f32_e32 v10, 1.0, v11
	v_mul_f32_e32 v11, 0xbfb8aa3b, v93
	v_fmac_f32_e32 v92, v88, v96
	v_exp_f32_e32 v11, v11
	v_mul_f32_e32 v82, 0xbfb8aa3b, v84
	v_mul_f32_e32 v83, 0xbfb8aa3b, v92
	v_exp_f32_e32 v82, v82
	v_exp_f32_e32 v83, v83
	v_add_f32_e32 v11, 1.0, v11
; __device__ __forceinline__ unsigned pk2(float lo, float hi) { return pg8::cvt_pk_bf16(lo, hi); }
; __device__ __forceinline__ void prepR_phase(const Params& P, int wid, int G, int NGW, int lane) {
;     ...
;         for (int ks = 0; ks < 8; ++ks) {
;             const int col = 32 * ks + 8 * fq; float p[8], pp[8]; ld8(PX + (size_t)row * 256 + col, true, p); ld8(PX + (size_t)(prow < 0 ? 0 : prow) * 256 + col, prow >= 0, pp);
;             const f32x4 m0 = *(const f32x4*)(mu + 1536 + col), m1 = *(const f32x4*)(mu + 1536 + col + 4); float x[8];
; #pragma unroll
;             for (int e = 0; e < 8; ++e) { const float m = e < 4 ? m0[e & 3] : m1[e & 3]; x[e] = p[e] + (pp[e] - p[e]) * m; }
;             if (ks < 2) {
; #pragma unroll
;                 for (int e = 0; e < 8; ++e) { const float t = __expf(-2.0f * __builtin_fabsf(x[e])); const float th = (1.0f - t) * __builtin_amdgcn_rcpf(1.0f + t); x[e] = x[e] < 0.f ? -th : th; }
;             } else if (ks >= 4) {
; #pragma unroll
;                 for (int e = 0; e < 8; ++e) x[e] = __builtin_amdgcn_rcpf(1.0f + __expf(-x[e]));
;             }
;             const u32x4 w = (u32x4){pk2(x[0], x[1]), pk2(x[2], x[3]), pk2(x[4], x[5]), pk2(x[6], x[7])};
;             const bf16x8 f = __builtin_bit_cast(bf16x8, w);
;             if (ks < 2) xwf[ks] = f; else if (ks < 4) xaf[ks - 2] = f; else xgf[ks - 4] = f;
	v_rcp_f32_e32 v10, v10
	v_rcp_f32_e32 v11, v11
	v_rcp_f32_e32 v84, v9
	v_rcp_f32_e32 v85, v8
	v_add_f32_e32 v82, 1.0, v82
	v_add_f32_e32 v83, 1.0, v83
	v_rcp_f32_e32 v82, v82
	v_rcp_f32_e32 v83, v83
	v_cvt_pk_bf16_f32 v9, v11, v10
	v_cvt_pk_bf16_f32 v10, v84, v81
	v_cvt_pk_bf16_f32 v11, v85, v80
	v_lshlrev_b32_e32 v80, 16, v72
	v_and_b32_e32 v81, 0xffff0000, v72
	v_lshlrev_b32_e32 v72, 16, v73
	v_and_b32_e32 v73, 0xffff0000, v73
	v_lshlrev_b32_e32 v84, 16, v12
	v_and_b32_e32 v85, 0xffff0000, v12
	v_lshlrev_b32_e32 v12, 16, v13
	v_and_b32_e32 v13, 0xffff0000, v13
	v_pk_add_f32 v[12:13], v[12:13], v[72:73] neg_lo:[0,1] neg_hi:[0,1]
	v_cvt_pk_bf16_f32 v8, v83, v82
	v_lshlrev_b32_e32 v82, 16, v74
	v_and_b32_e32 v83, 0xffff0000, v74
	v_pk_fma_f32 v[72:73], v[78:79], v[12:13], v[72:73]
	v_lshlrev_b32_e32 v12, 16, v14
	v_and_b32_e32 v13, 0xffff0000, v14
	v_pk_add_f32 v[12:13], v[12:13], v[82:83] neg_lo:[0,1] neg_hi:[0,1]
	v_lshlrev_b32_e32 v74, 16, v75
	v_and_b32_e32 v75, 0xffff0000, v75
	v_pk_fma_f32 v[68:69], v[68:69], v[12:13], v[82:83]
	v_lshlrev_b32_e32 v12, 16, v15
	v_and_b32_e32 v13, 0xffff0000, v15
	v_pk_add_f32 v[12:13], v[12:13], v[74:75] neg_lo:[0,1] neg_hi:[0,1]
	v_cvt_pk_bf16_f32 v14, v68, v69
	v_pk_fma_f32 v[70:71], v[70:71], v[12:13], v[74:75]
	v_cvt_pk_bf16_f32 v13, v72, v73
	v_lshlrev_b32_e32 v68, 16, v60
	v_and_b32_e32 v69, 0xffff0000, v60
	v_lshlrev_b32_e32 v60, 16, v61
	v_and_b32_e32 v61, 0xffff0000, v61
	v_lshlrev_b32_e32 v72, 16, v16
	v_and_b32_e32 v73, 0xffff0000, v16
	v_lshlrev_b32_e32 v16, 16, v17
	v_and_b32_e32 v17, 0xffff0000, v17
	v_pk_add_f32 v[16:17], v[16:17], v[60:61] neg_lo:[0,1] neg_hi:[0,1]
	v_cvt_pk_bf16_f32 v15, v70, v71
	v_lshlrev_b32_e32 v70, 16, v62
	v_and_b32_e32 v71, 0xffff0000, v62
	v_pk_fma_f32 v[60:61], v[66:67], v[16:17], v[60:61]
	v_lshlrev_b32_e32 v16, 16, v18
	v_and_b32_e32 v17, 0xffff0000, v18
	v_pk_add_f32 v[16:17], v[16:17], v[70:71] neg_lo:[0,1] neg_hi:[0,1]
	v_lshlrev_b32_e32 v62, 16, v63
	v_and_b32_e32 v63, 0xffff0000, v63
	v_pk_fma_f32 v[56:57], v[56:57], v[16:17], v[70:71]
	v_lshlrev_b32_e32 v16, 16, v19
	v_and_b32_e32 v17, 0xffff0000, v19
	v_pk_add_f32 v[16:17], v[16:17], v[62:63] neg_lo:[0,1] neg_hi:[0,1]
	v_cvt_pk_bf16_f32 v18, v56, v57
	v_pk_fma_f32 v[58:59], v[58:59], v[16:17], v[62:63]
	v_cvt_pk_bf16_f32 v17, v60, v61
	v_cvt_pk_bf16_f32 v19, v58, v59
	v_lshlrev_b32_e32 v58, 16, v51
	v_and_b32_e32 v59, 0xffff0000, v51
	v_lshlrev_b32_e32 v60, 16, v23
	v_and_b32_e32 v61, 0xffff0000, v23
	v_pk_add_f32 v[60:61], v[60:61], v[58:59] neg_lo:[0,1] neg_hi:[0,1]
	v_lshlrev_b32_e32 v62, 16, v50
	v_pk_fma_f32 v[54:55], v[54:55], v[60:61], v[58:59]
	v_and_b32_e32 v63, 0xffff0000, v50
	v_mul_f32_e64 v23, |v55|, -2.0
	v_mul_f32_e32 v23, 0x3fb8aa3b, v23
	v_exp_f32_e32 v59, v23
	v_mul_f32_e64 v23, |v54|, -2.0
	v_mul_f32_e32 v23, 0x3fb8aa3b, v23
	v_exp_f32_e32 v58, v23
	v_add_f32_e32 v23, 1.0, v59
	v_rcp_f32_e32 v61, v23
	v_cmp_gt_f32_e64 s[0:1], 0, v55
	v_add_f32_e32 v23, 1.0, v58
	v_pk_add_f32 v[50:51], v[58:59], 1.0 op_sel_hi:[1,0] neg_lo:[1,0] neg_hi:[1,0]
	v_lshlrev_b32_e32 v58, 16, v22
	v_and_b32_e32 v59, 0xffff0000, v22
	v_rcp_f32_e32 v60, v23
	v_pk_add_f32 v[22:23], v[58:59], v[62:63] neg_lo:[0,1] neg_hi:[0,1]
	v_lshlrev_b32_e32 v56, 16, v48
	v_pk_fma_f32 v[22:23], v[52:53], v[22:23], v[62:63]
	v_pk_mul_f32 v[50:51], v[50:51], v[60:61]
	v_mul_f32_e64 v52, |v23|, -2.0
	v_mul_f32_e32 v52, 0x3fb8aa3b, v52
	v_exp_f32_e32 v53, v52
	v_mul_f32_e64 v52, |v22|, -2.0
	v_mul_f32_e32 v52, 0x3fb8aa3b, v52
	v_exp_f32_e32 v52, v52
	v_cndmask_b32_e64 v55, v51, -v51, s[0:1]
	v_add_f32_e32 v51, 1.0, v53
	v_rcp_f32_e32 v59, v51
	v_add_f32_e32 v51, 1.0, v52
	v_cmp_gt_f32_e64 s[0:1], 0, v54
	v_and_b32_e32 v57, 0xffff0000, v48
	v_lshlrev_b32_e32 v48, 16, v49
	v_and_b32_e32 v49, 0xffff0000, v49
	v_rcp_f32_e32 v58, v51
	v_cndmask_b32_e64 v54, v50, -v50, s[0:1]
	v_pk_add_f32 v[50:51], v[52:53], 1.0 op_sel_hi:[1,0] neg_lo:[1,0] neg_hi:[1,0]
	v_lshlrev_b32_e32 v52, 16, v21
	v_and_b32_e32 v53, 0xffff0000, v21
	v_pk_add_f32 v[52:53], v[52:53], v[48:49] neg_lo:[0,1] neg_hi:[0,1]
	v_pk_mul_f32 v[50:51], v[50:51], v[58:59]
	v_pk_fma_f32 v[46:47], v[46:47], v[52:53], v[48:49]
	v_cmp_gt_f32_e64 s[0:1], 0, v23
	v_mul_f32_e64 v21, |v47|, -2.0
	v_mul_f32_e32 v21, 0x3fb8aa3b, v21
	v_exp_f32_e32 v49, v21
	v_mul_f32_e64 v21, |v46|, -2.0
	v_mul_f32_e32 v21, 0x3fb8aa3b, v21
	v_exp_f32_e32 v48, v21
	v_add_f32_e32 v21, 1.0, v49
	v_cndmask_b32_e64 v51, v51, -v51, s[0:1]
	v_rcp_f32_e32 v53, v21
	v_add_f32_e32 v21, 1.0, v48
	v_cmp_gt_f32_e64 s[0:1], 0, v22
	v_pk_add_f32 v[22:23], v[48:49], 1.0 op_sel_hi:[1,0] neg_lo:[1,0] neg_hi:[1,0]
	v_lshlrev_b32_e32 v48, 16, v20
	v_and_b32_e32 v49, 0xffff0000, v20
	v_rcp_f32_e32 v52, v21
	v_pk_add_f32 v[20:21], v[48:49], v[56:57] neg_lo:[0,1] neg_hi:[0,1]
	v_cndmask_b32_e64 v50, v50, -v50, s[0:1]
	v_pk_fma_f32 v[20:21], v[44:45], v[20:21], v[56:57]
	v_pk_mul_f32 v[22:23], v[22:23], v[52:53]
	v_mul_f32_e64 v44, |v21|, -2.0
	v_mul_f32_e32 v44, 0x3fb8aa3b, v44
	v_exp_f32_e32 v45, v44
	v_mul_f32_e64 v44, |v20|, -2.0
	v_mul_f32_e32 v44, 0x3fb8aa3b, v44
	v_exp_f32_e32 v44, v44
	v_cmp_gt_f32_e64 s[0:1], 0, v47
	v_mul_f32_e32 v111, 0xbfb8aa3b, v122
	v_exp_f32_e32 v110, v110
	v_cndmask_b32_e64 v47, v23, -v23, s[0:1]
	v_add_f32_e32 v23, 1.0, v45
	v_rcp_f32_e32 v49, v23
	v_add_f32_e32 v23, 1.0, v44
	v_rcp_f32_e32 v48, v23
	v_cmp_gt_f32_e64 s[0:1], 0, v46
	v_exp_f32_e32 v111, v111
	v_add_f32_e32 v110, 1.0, v110
	v_cndmask_b32_e64 v46, v22, -v22, s[0:1]
	v_pk_add_f32 v[22:23], v[44:45], 1.0 op_sel_hi:[1,0] neg_lo:[1,0] neg_hi:[1,0]
	v_cmp_gt_f32_e64 s[0:1], 0, v21
	v_pk_mul_f32 v[22:23], v[22:23], v[48:49]
; __device__ __forceinline__ unsigned pk2(float lo, float hi) { return pg8::cvt_pk_bf16(lo, hi); }
; __device__ __forceinline__ void prepR_phase(const Params& P, int wid, int G, int NGW, int lane) {
;     ...
;         for (int ks = 0; ks < 8; ++ks) {
;             const int col = 32 * ks + 8 * fq; float p[8], pp[8]; ld8(PX + (size_t)row * 256 + col, true, p); ld8(PX + (size_t)(prow < 0 ? 0 : prow) * 256 + col, prow >= 0, pp);
;             const f32x4 m0 = *(const f32x4*)(mu + 1536 + col), m1 = *(const f32x4*)(mu + 1536 + col + 4); float x[8];
; #pragma unroll
;             for (int e = 0; e < 8; ++e) { const float m = e < 4 ? m0[e & 3] : m1[e & 3]; x[e] = p[e] + (pp[e] - p[e]) * m; }
;             if (ks < 2) {
; #pragma unroll
;                 for (int e = 0; e < 8; ++e) { const float t = __expf(-2.0f * __builtin_fabsf(x[e])); const float th = (1.0f - t) * __builtin_amdgcn_rcpf(1.0f + t); x[e] = x[e] < 0.f ? -th : th; }
;             } else if (ks >= 4) {
; #pragma unroll
;                 for (int e = 0; e < 8; ++e) x[e] = __builtin_amdgcn_rcpf(1.0f + __expf(-x[e]));
;             }
;             const u32x4 w = (u32x4){pk2(x[0], x[1]), pk2(x[2], x[3]), pk2(x[4], x[5]), pk2(x[6], x[7])};
;             const bf16x8 f = __builtin_bit_cast(bf16x8, w);
;             if (ks < 2) xwf[ks] = f; else if (ks < 4) xaf[ks - 2] = f; else xgf[ks - 4] = f;
	v_lshlrev_b32_e32 v48, 16, v35
	v_cndmask_b32_e64 v21, v23, -v23, s[0:1]
	v_cmp_gt_f32_e64 s[0:1], 0, v20
	v_and_b32_e32 v49, 0xffff0000, v35
	v_lshlrev_b32_e32 v44, 16, v32
	v_cndmask_b32_e64 v20, v22, -v22, s[0:1]
	v_cvt_pk_bf16_f32 v22, v50, v51
	v_lshlrev_b32_e32 v50, 16, v27
	v_and_b32_e32 v51, 0xffff0000, v27
	v_pk_add_f32 v[50:51], v[50:51], v[48:49] neg_lo:[0,1] neg_hi:[0,1]
	v_cvt_pk_bf16_f32 v20, v20, v21
	v_pk_fma_f32 v[48:49], v[42:43], v[50:51], v[48:49]
	v_cvt_pk_bf16_f32 v21, v46, v47
	v_mul_f32_e64 v27, |v49|, -2.0
	v_mul_f32_e32 v27, 0x3fb8aa3b, v27
	v_exp_f32_e32 v43, v27
	v_mul_f32_e64 v27, |v48|, -2.0
	v_mul_f32_e32 v27, 0x3fb8aa3b, v27
	v_exp_f32_e32 v42, v27
	v_add_f32_e32 v27, 1.0, v43
	v_lshlrev_b32_e32 v46, 16, v33
	v_and_b32_e32 v47, 0xffff0000, v33
	v_rcp_f32_e32 v33, v27
	v_add_f32_e32 v27, 1.0, v42
	v_and_b32_e32 v45, 0xffff0000, v32
	v_rcp_f32_e32 v32, v27
	v_lshlrev_b32_e32 v50, 16, v34
	v_and_b32_e32 v51, 0xffff0000, v34
	v_pk_add_f32 v[34:35], v[42:43], 1.0 op_sel_hi:[1,0] neg_lo:[1,0] neg_hi:[1,0]
	v_cmp_gt_f32_e64 s[0:1], 0, v49
	v_pk_mul_f32 v[52:53], v[34:35], v[32:33]
	v_lshlrev_b32_e32 v32, 16, v26
	v_and_b32_e32 v33, 0xffff0000, v26
	v_pk_add_f32 v[26:27], v[32:33], v[50:51] neg_lo:[0,1] neg_hi:[0,1]
	v_cvt_pk_bf16_f32 v23, v54, v55
	v_pk_fma_f32 v[26:27], v[40:41], v[26:27], v[50:51]
	global_load_dwordx4 v[32:35], v[164:165], off offset:16
	global_load_dwordx4 v[40:43], v[164:165], off
	v_mul_f32_e64 v50, |v27|, -2.0
	v_mul_f32_e32 v50, 0x3fb8aa3b, v50
	v_exp_f32_e32 v51, v50
	v_mul_f32_e64 v50, |v26|, -2.0
	v_mul_f32_e32 v50, 0x3fb8aa3b, v50
	v_exp_f32_e32 v50, v50
	v_add_f32_e32 v49, 1.0, v51
	v_rcp_f32_e32 v55, v49
	v_cndmask_b32_e64 v53, v53, -v53, s[0:1]
	v_add_f32_e32 v49, 1.0, v50
	v_rcp_f32_e32 v54, v49
	v_cmp_gt_f32_e64 s[0:1], 0, v48
	v_pk_add_f32 v[48:49], v[50:51], 1.0 op_sel_hi:[1,0] neg_lo:[1,0] neg_hi:[1,0]
	v_lshlrev_b32_e32 v50, 16, v25
	v_and_b32_e32 v51, 0xffff0000, v25
	v_pk_add_f32 v[50:51], v[50:51], v[46:47] neg_lo:[0,1] neg_hi:[0,1]
	v_cndmask_b32_e64 v52, v52, -v52, s[0:1]
	v_pk_fma_f32 v[30:31], v[30:31], v[50:51], v[46:47]
	v_pk_mul_f32 v[48:49], v[48:49], v[54:55]
	v_mul_f32_e64 v25, |v31|, -2.0
	v_mul_f32_e32 v25, 0x3fb8aa3b, v25
	v_exp_f32_e32 v47, v25
	v_mul_f32_e64 v25, |v30|, -2.0
	v_mul_f32_e32 v25, 0x3fb8aa3b, v25
	v_exp_f32_e32 v46, v25
	v_cmp_gt_f32_e64 s[0:1], 0, v27
	v_add_f32_e32 v25, 1.0, v47
	v_rcp_f32_e32 v51, v25
	v_cndmask_b32_e64 v49, v49, -v49, s[0:1]
	v_add_f32_e32 v25, 1.0, v46
	v_cmp_gt_f32_e64 s[0:1], 0, v26
	v_pk_add_f32 v[26:27], v[46:47], 1.0 op_sel_hi:[1,0] neg_lo:[1,0] neg_hi:[1,0]
	v_lshlrev_b32_e32 v46, 16, v24
	v_and_b32_e32 v47, 0xffff0000, v24
	v_rcp_f32_e32 v50, v25
	v_pk_add_f32 v[24:25], v[46:47], v[44:45] neg_lo:[0,1] neg_hi:[0,1]
	v_cndmask_b32_e64 v48, v48, -v48, s[0:1]
	v_pk_fma_f32 v[24:25], v[28:29], v[24:25], v[44:45]
	v_pk_mul_f32 v[26:27], v[26:27], v[50:51]
	v_mul_f32_e64 v28, |v25|, -2.0
	v_mul_f32_e32 v28, 0x3fb8aa3b, v28
	v_exp_f32_e32 v29, v28
	v_mul_f32_e64 v28, |v24|, -2.0
	v_mul_f32_e32 v28, 0x3fb8aa3b, v28
	v_exp_f32_e32 v28, v28
	v_cmp_gt_f32_e64 s[0:1], 0, v31
	v_add_f32_e32 v111, 1.0, v111
	v_rcp_f32_e32 v110, v110
	v_cndmask_b32_e64 v31, v27, -v27, s[0:1]
	v_add_f32_e32 v27, 1.0, v29
	v_rcp_f32_e32 v45, v27
	v_add_f32_e32 v27, 1.0, v28
	v_rcp_f32_e32 v44, v27
	v_cmp_gt_f32_e64 s[0:1], 0, v30
	v_rcp_f32_e32 v111, v111
	v_lshlrev_b32_e32 v108, 16, v104
	v_cndmask_b32_e64 v30, v26, -v26, s[0:1]
	v_pk_add_f32 v[26:27], v[28:29], 1.0 op_sel_hi:[1,0] neg_lo:[1,0] neg_hi:[1,0]
	v_cmp_gt_f32_e64 s[0:1], 0, v25
	v_pk_mul_f32 v[26:27], v[26:27], v[44:45]
	v_lshlrev_b32_e32 v28, 16, v36
	v_cndmask_b32_e64 v25, v27, -v27, s[0:1]
	v_cmp_gt_f32_e64 s[0:1], 0, v24
	v_cvt_pk_bf16_f32 v0, v111, v110
	v_and_b32_e32 v104, 0xffff0000, v104
	v_cndmask_b32_e64 v24, v26, -v26, s[0:1]
	v_lshlrev_b32_e32 v111, 16, v107
	v_cvt_pk_bf16_f32 v24, v24, v25
	v_cvt_pk_bf16_f32 v25, v30, v31
	v_and_b32_e32 v29, 0xffff0000, v36
	v_lshlrev_b32_e32 v30, 16, v37
	v_and_b32_e32 v31, 0xffff0000, v37
	v_lshlrev_b32_e32 v36, 16, v38
	v_and_b32_e32 v37, 0xffff0000, v38
	v_lshlrev_b32_e32 v38, 16, v39
	v_sub_f32_e32 v28, v28, v108
	v_and_b32_e32 v107, 0xffff0000, v107
	v_and_b32_e32 v39, 0xffff0000, v39
	v_lshlrev_b32_e32 v109, 16, v105
	s_waitcnt vmcnt(0)
; __device__ __forceinline__ void prepR_phase(const Params& P, int wid, int G, int NGW, int lane) {
;     ...
;     for (int it = wid * G + (int)blockIdx.x; it < (MMAIN / 16) * 2 + 8; it += NGW) {
;         const bool mt = it >= (MMAIN / 16) * 2; const int h0 = mt ? it - (MMAIN / 16) * 2 : 4 * (it & 1), nh = mt ? 1 : 4; const int row_raw = (mt ? MMAIN : 16 * (it >> 1)) + fr; const bool valid = row_raw < MVALID; const int row = valid ? row_raw : 0;
;         const int prow = (row >= MMAIN) ? (row == MMAIN ? -1 : row - 1) : ((row & (SEQ - 1)) == 0 ? MVALID - 1 : row - 1);
;     ...
;         for (int h = h0; h < h0 + nh; ++h) {
;             f32x4 wacc[4], aacc[4], gacc[4];
; #pragma unroll
;             for (int nt = 0; nt < 4; ++nt) {
;                 wacc[nt] = (f32x4){0.f, 0.f, 0.f, 0.f}; aacc[nt] = wacc[nt]; gacc[nt] = wacc[nt];
;                 const int chr = h * 64 + 16 * (fr >> 2) + 4 * nt + (fr & 3);
; #pragma unroll
;                 for (int ks = 0; ks < 2; ++ks) {
;                     const bf16x8 bw = *(const bf16x8*)(LW + (size_t)chr * 64 + 32 * ks + 8 * fq), ba = *(const bf16x8*)(LA + (size_t)chr * 64 + 32 * ks + 8 * fq);
;                     wacc[nt] = __builtin_amdgcn_mfma_f32_16x16x32_bf16(bw, xwf[ks], wacc[nt], 0, 0, 0);
;                     aacc[nt] = __builtin_amdgcn_mfma_f32_16x16x32_bf16(ba, xaf[ks], aacc[nt], 0, 0, 0);
;                 }
; #pragma unroll
;                 for (int ks = 0; ks < 4; ++ks) {
;                     const bf16x8 bg = *(const bf16x8*)(LG + (size_t)chr * 128 + 32 * ks + 8 * fq);
;                     gacc[nt] = __builtin_amdgcn_mfma_f32_16x16x32_bf16(bg, xgf[ks], gacc[nt], 0, 0, 0);
;                 }
;             }
;             float kk[4][4], as[4][4], sskk = 0.f, bon = 0.f;
;             const int col16 = h * 64 + 16 * fq;
	v_fmac_f32_e32 v108, v40, v28
	v_sub_f32_e32 v28, v29, v104
	v_sub_f32_e32 v29, v38, v111
	v_fmac_f32_e32 v111, v34, v29
	v_sub_f32_e32 v29, v39, v107
	v_fmac_f32_e32 v107, v35, v29
	v_and_b32_e32 v105, 0xffff0000, v105
	v_fmac_f32_e32 v104, v41, v28
	v_sub_f32_e32 v28, v30, v109
	v_mul_f32_e32 v29, 0xbfb8aa3b, v107
	v_lshlrev_b32_e32 v110, 16, v106
	v_fmac_f32_e32 v109, v42, v28
	v_sub_f32_e32 v28, v31, v105
	v_exp_f32_e32 v29, v29
	v_mul_f32_e32 v30, 0xbfb8aa3b, v111
	v_and_b32_e32 v106, 0xffff0000, v106
	v_fmac_f32_e32 v105, v43, v28
	v_sub_f32_e32 v28, v36, v110
	v_exp_f32_e32 v30, v30
	v_fmac_f32_e32 v110, v32, v28
	v_sub_f32_e32 v28, v37, v106
	v_fmac_f32_e32 v106, v33, v28
	v_add_f32_e32 v28, 1.0, v29
	v_mul_f32_e32 v29, 0xbfb8aa3b, v106
	v_rcp_f32_e32 v31, v28
	v_add_f32_e32 v28, 1.0, v30
	v_exp_f32_e32 v29, v29
	v_mul_f32_e32 v30, 0xbfb8aa3b, v110
	v_mul_f32_e32 v32, 0xbfb8aa3b, v105
	v_exp_f32_e32 v30, v30
	v_exp_f32_e32 v32, v32
	v_add_f32_e32 v29, 1.0, v29
	v_rcp_f32_e32 v33, v29
	v_add_f32_e32 v29, 1.0, v30
	v_add_f32_e32 v30, 1.0, v32
	v_mul_f32_e32 v32, 0xbfb8aa3b, v109
	v_exp_f32_e32 v32, v32
	v_mul_f32_e32 v34, 0xbfb8aa3b, v104
	v_mul_f32_e32 v35, 0xbfb8aa3b, v108
	v_exp_f32_e32 v34, v34
	v_exp_f32_e32 v35, v35
	s_lshl_b32 s0, s30, 2
	v_add_f32_e32 v32, 1.0, v32
	s_add_i32 s28, s30, 0xfffff800
	s_and_b32 s100, s28, 1
	s_lshr_b32 s28, s28, 1
	s_lshl_b32 s100, s100, 2
	s_add_i32 s28, s28, s100
	s_and_b32 s29, s0, 4
	v_rcp_f32_e32 v30, v30
	v_rcp_f32_e32 v32, v32
	v_rcp_f32_e32 v36, v29
	s_and_b64 s[0:1], s[4:5], exec
	s_cselect_b32 s28, s28, s29
	v_add_f32_e32 v34, 1.0, v34
	v_add_f32_e32 v35, 1.0, v35
	s_cselect_b32 s0, 1, 4
	s_mov_b32 s101, s0
	v_rcp_f32_e32 v34, v34
	v_rcp_f32_e32 v35, v35
	v_rcp_f32_e32 v37, v28
	s_ashr_i32 s29, s28, 31
	v_cvt_pk_bf16_f32 v29, v32, v30
	v_cvt_pk_bf16_f32 v30, v36, v33
	s_add_i32 s56, s28, s0
	v_lshlrev_b64 v[32:33], 1, v[170:171]
	v_max_i32_e32 v142, 0, v142
	s_lshl_b64 s[0:1], s[28:29], 2
	v_pk_add_f32 v[84:85], v[84:85], v[80:81] neg_lo:[0,1] neg_hi:[0,1]
	v_pk_add_f32 v[72:73], v[72:73], v[68:69] neg_lo:[0,1] neg_hi:[0,1]
	v_lshl_add_u64 v[172:173], s[6:7], 0, v[32:33]
	v_lshl_add_u64 v[174:175], s[8:9], 0, v[32:33]
	v_lshl_add_u64 v[176:177], s[10:11], 0, v[32:33]
	v_lshlrev_b64 v[32:33], 10, v[142:143]
	s_add_u32 s0, s31, s0
	v_pk_fma_f32 v[76:77], v[76:77], v[84:85], v[80:81]
	v_pk_fma_f32 v[64:65], v[64:65], v[72:73], v[68:69]
	v_lshl_add_u64 v[178:179], s[6:7], 0, v[32:33]
	v_lshl_add_u64 v[180:181], s[8:9], 0, v[32:33]
	v_lshl_add_u64 v[182:183], s[10:11], 0, v[32:33]
	v_lshlrev_b64 v[32:33], 5, v[120:121]
	s_addc_u32 s1, s34, s1
	v_cvt_pk_bf16_f32 v12, v76, v77
	v_cvt_pk_bf16_f32 v16, v64, v65
	v_cvt_pk_bf16_f32 v26, v48, v49
	v_cvt_pk_bf16_f32 v27, v52, v53
	v_cvt_pk_bf16_f32 v28, v35, v34
	v_cvt_pk_bf16_f32 v31, v37, v31
	v_lshl_add_u64 v[184:185], s[0:1], 0, v[32:33]
	s_lshl_b32 s29, s28, 6
	s_cmp_eq_u32 s101, 1
	s_cbranch_scc1 .Lmy_lora_nobar
	s_waitcnt vmcnt(0)
	s_barrier

; __device__ __forceinline__ void prepR_phase(const Params& P, int wid, int G, int NGW, int lane) {
;     ...
;         for (int h = h0; h < h0 + nh; ++h) {
;             f32x4 wacc[4], aacc[4], gacc[4];
; #pragma unroll
;             for (int nt = 0; nt < 4; ++nt) {
;                 wacc[nt] = (f32x4){0.f, 0.f, 0.f, 0.f}; aacc[nt] = wacc[nt]; gacc[nt] = wacc[nt];
;                 const int chr = h * 64 + 16 * (fr >> 2) + 4 * nt + (fr & 3);
; #pragma unroll
;                 for (int ks = 0; ks < 2; ++ks) {
;                     const bf16x8 bw = *(const bf16x8*)(LW + (size_t)chr * 64 + 32 * ks + 8 * fq), ba = *(const bf16x8*)(LA + (size_t)chr * 64 + 32 * ks + 8 * fq);
;                     wacc[nt] = __builtin_amdgcn_mfma_f32_16x16x32_bf16(bw, xwf[ks], wacc[nt], 0, 0, 0);
;                     aacc[nt] = __builtin_amdgcn_mfma_f32_16x16x32_bf16(ba, xaf[ks], aacc[nt], 0, 0, 0);
;                 }
; #pragma unroll
;                 for (int ks = 0; ks < 4; ++ks) {
;                     const bf16x8 bg = *(const bf16x8*)(LG + (size_t)chr * 128 + 32 * ks + 8 * fq);
;                     gacc[nt] = __builtin_amdgcn_mfma_f32_16x16x32_bf16(bg, xgf[ks], gacc[nt], 0, 0, 0);
;                 }
;             }
.LBB0_765:
	v_add_u32_e32 v188, s29, v237
	s_and_b32 s0, s33, 1
	s_lshl_b32 s0, s0, 8
	s_sub_i32 s0, s29, s0
	v_ashrrev_i32_e32 v189, 31, v188
	v_add_u32_e32 v88, s0, v240
	v_lshlrev_b32_e32 v89, 3, v236
	v_lshl_add_u64 v[210:211], v[188:189], 1, v[172:173]
	v_and_b32_e32 v89, 0x70, v89
	v_lshlrev_b32_e32 v104, 4, v236
	global_load_dwordx4 v[56:59], v[210:211], off
	v_xor_b32_e32 v89, v237, v89
	v_xor_b32_e32 v104, v237, v104
	v_lshl_add_u32 v102, v88, 7, v89
	v_lshl_add_u32 v88, v88, 8, v104
	v_xor_b32_e32 v103, 64, v102
	v_add_u32_e32 v88, 0x10000, v88
	v_lshl_add_u64 v[214:215], v[188:189], 1, v[178:179]
	v_xor_b32_e32 v104, 64, v88
	v_xor_b32_e32 v105, 0x80, v88
	v_xor_b32_e32 v89, 0xc0, v88
	ds_read_b128 v[60:63], v102 offset:0
	ds_read_b128 v[64:67], v102 offset:512
	ds_read_b128 v[68:71], v102 offset:1024
	ds_read_b128 v[72:75], v102 offset:1536
	ds_read_b128 v[76:79], v102 offset:32768
	ds_read_b128 v[80:83], v102 offset:33280
	ds_read_b128 v[84:87], v102 offset:33792
	ds_read_b128 v[118:121], v102 offset:34304
	s_waitcnt lgkmcnt(7)
	v_mfma_f32_16x16x32_bf16 v[114:117], v[60:63], v[24:27], 0
	ds_read_b128 v[60:63], v88 offset:0
	s_waitcnt lgkmcnt(7)
	v_mfma_f32_16x16x32_bf16 v[106:109], v[64:67], v[24:27], 0
	ds_read_b128 v[64:67], v88 offset:1024
	s_waitcnt lgkmcnt(7)
	v_mfma_f32_16x16x32_bf16 v[52:55], v[68:71], v[24:27], 0
	ds_read_b128 v[68:71], v88 offset:2048
	s_waitcnt lgkmcnt(7)
	v_mfma_f32_16x16x32_bf16 v[44:47], v[72:75], v[24:27], 0
	ds_read_b128 v[72:75], v88 offset:3072
	s_waitcnt lgkmcnt(7)
	v_mfma_f32_16x16x32_bf16 v[110:113], v[76:79], v[16:19], 0
	ds_read_b128 v[76:79], v103 offset:0
	s_waitcnt lgkmcnt(7)
	v_mfma_f32_16x16x32_bf16 v[98:101], v[80:83], v[16:19], 0
	ds_read_b128 v[80:83], v103 offset:512
	s_waitcnt lgkmcnt(7)
	v_mfma_f32_16x16x32_bf16 v[48:51], v[84:87], v[16:19], 0
	ds_read_b128 v[84:87], v103 offset:1024
	s_waitcnt lgkmcnt(7)
	v_mfma_f32_16x16x32_bf16 v[40:43], v[118:121], v[16:19], 0
	ds_read_b128 v[118:121], v103 offset:1536
	s_waitcnt lgkmcnt(7)
	v_mfma_f32_16x16x32_bf16 v[90:93], v[60:63], v[8:11], 0
	ds_read_b128 v[60:63], v103 offset:32768
	s_waitcnt lgkmcnt(7)
	v_mfma_f32_16x16x32_bf16 v[94:97], v[64:67], v[8:11], 0
	ds_read_b128 v[64:67], v103 offset:33280
	s_waitcnt lgkmcnt(7)
	v_mfma_f32_16x16x32_bf16 v[32:35], v[68:71], v[8:11], 0
	ds_read_b128 v[68:71], v103 offset:33792
	s_waitcnt lgkmcnt(7)
	v_mfma_f32_16x16x32_bf16 v[36:39], v[72:75], v[8:11], 0
	ds_read_b128 v[72:75], v103 offset:34304
	s_waitcnt lgkmcnt(7)
	v_mfma_f32_16x16x32_bf16 v[114:117], v[76:79], v[20:23], v[114:117]
	ds_read_b128 v[76:79], v104 offset:0
	s_waitcnt lgkmcnt(7)
	v_mfma_f32_16x16x32_bf16 v[106:109], v[80:83], v[20:23], v[106:109]
	ds_read_b128 v[80:83], v104 offset:1024
	s_waitcnt lgkmcnt(7)
	v_mfma_f32_16x16x32_bf16 v[52:55], v[84:87], v[20:23], v[52:55]
	ds_read_b128 v[84:87], v104 offset:2048
	s_waitcnt lgkmcnt(7)
	v_mfma_f32_16x16x32_bf16 v[44:47], v[118:121], v[20:23], v[44:47]
	ds_read_b128 v[118:121], v104 offset:3072
	s_waitcnt lgkmcnt(7)
	v_mfma_f32_16x16x32_bf16 v[110:113], v[60:63], v[12:15], v[110:113]
	ds_read_b128 v[60:63], v105 offset:0
	s_waitcnt lgkmcnt(7)
	v_mfma_f32_16x16x32_bf16 v[98:101], v[64:67], v[12:15], v[98:101]
	ds_read_b128 v[64:67], v105 offset:1024
	s_waitcnt lgkmcnt(7)
	v_mfma_f32_16x16x32_bf16 v[48:51], v[68:71], v[12:15], v[48:51]
	ds_read_b128 v[68:71], v105 offset:2048
	s_waitcnt lgkmcnt(7)
	v_mfma_f32_16x16x32_bf16 v[40:43], v[72:75], v[12:15], v[40:43]
	ds_read_b128 v[72:75], v105 offset:3072
	s_waitcnt lgkmcnt(7)
	v_mfma_f32_16x16x32_bf16 v[90:93], v[76:79], v[4:7], v[90:93]
	ds_read_b128 v[76:79], v89 offset:0
	s_waitcnt lgkmcnt(7)
	v_mfma_f32_16x16x32_bf16 v[94:97], v[80:83], v[4:7], v[94:97]
	ds_read_b128 v[80:83], v89 offset:1024
	s_waitcnt lgkmcnt(7)
	v_mfma_f32_16x16x32_bf16 v[32:35], v[84:87], v[4:7], v[32:35]
	ds_read_b128 v[84:87], v89 offset:2048
	s_waitcnt lgkmcnt(7)
	v_mfma_f32_16x16x32_bf16 v[36:39], v[118:121], v[4:7], v[36:39]
	ds_read_b128 v[118:121], v89 offset:3072
	s_waitcnt lgkmcnt(7)
	v_mfma_f32_16x16x32_bf16 v[90:93], v[60:63], v[0:3], v[90:93]
	s_waitcnt lgkmcnt(6)
	v_mfma_f32_16x16x32_bf16 v[94:97], v[64:67], v[0:3], v[94:97]
	s_waitcnt lgkmcnt(5)
	v_mfma_f32_16x16x32_bf16 v[32:35], v[68:71], v[0:3], v[32:35]
	s_waitcnt lgkmcnt(4)
	v_mfma_f32_16x16x32_bf16 v[36:39], v[72:75], v[0:3], v[36:39]
	s_waitcnt lgkmcnt(3)
	v_mfma_f32_16x16x32_bf16 v[90:93], v[76:79], v[28:31], v[90:93]
	s_waitcnt lgkmcnt(2)
	v_mfma_f32_16x16x32_bf16 v[94:97], v[80:83], v[28:31], v[94:97]
	s_waitcnt lgkmcnt(1)
	v_mfma_f32_16x16x32_bf16 v[32:35], v[84:87], v[28:31], v[32:35]
	s_waitcnt lgkmcnt(0)
	v_mfma_f32_16x16x32_bf16 v[36:39], v[118:121], v[28:31], v[36:39]
	s_nop 7
	v_mov_b32_e32 v72, 0
	v_mov_b32_e32 v60, 0
	v_mov_b32_e32 v61, 0
	v_mov_b32_e32 v62, 0
	v_mov_b32_e32 v63, 0
	s_nop 7
	s_waitcnt vmcnt(0)
	s_branch .Lmy_lora_join

; #define LAS __attribute__((address_space(3)))
; __device__ __forceinline__ void scan_phase(const Params& P, LAS unsigned char* lds, int tid, int wid, int lane) {
;     ...
;                 const LAS unsigned char* buf = lds + (ck & 1) * SBUF + jq * 16; const LAS unsigned char* vbuf = lds + (ck & 1) * SBUF + 1280 + il * 4; const LAS unsigned char* sbuf = lds + (ck & 1) * SBUF + 1600;
;                 LAS float* yb = (LAS float*)(lds + YOFF + (ck & 1) * 2048);
;                 f32x4 w0[2], kh0[2], kk0[2], b0[2], r0[2], wk0[2], w1[2], kh1[2], b1[2], r1[2]; float v0[2], v1[2]; f32x2v bk[2];
;     ...
;                 SC_LOADP(0, 0);
.LBB0_879:
	s_andn2_b64 vcc, exec, s[12:13]
	s_cbranch_vccnz .LBB0_858
	s_and_b32 s12, s31, 1
	s_mul_i32 s13, s12, 0xca00
	s_add_i32 s36, s13, 0
	v_add_u32_e32 v1, s36, v48
	s_waitcnt vmcnt(3)
	ds_read_b128 v[14:17], v1
	s_waitcnt vmcnt(1)
	ds_read_b128 v[22:25], v1 offset:256
	ds_read_b128 v[42:45], v1 offset:512
	ds_read_b128 v[6:9], v1 offset:1024
	ds_read_b128 v[38:41], v1 offset:1344
	ds_read_b128 v[18:21], v1 offset:1616
	s_waitcnt vmcnt(0)
	ds_read_b128 v[26:29], v1 offset:1872
	ds_read_b128 v[10:13], v1 offset:2640
	v_lshl_add_u32 v63, v134, 2, s36
	v_mov_b32_e32 v65, s36
	ds_read_b128 v[108:111], v63 offset:2960
	v_lshl_add_u32 v65, s12, 11, v135
	s_mov_b32 s37, 0
	s_mov_b64 s[12:13], -1
